# diff-attn combine: all 64 partial-O loads hoisted (one round trip), 8 trips unrolled, ds_bpermute butterfly replaced by DPP row reduce + readlane
# baseline (speedup 1.0000x reference)
.LBB0_478:
	v_add_co_u32_e32 v12, vcc, 0xfffdd000, v4
	global_load_dwordx2 v[40:41], v[4:5], off offset:-4096
	global_load_dwordx2 v[42:43], v[4:5], off
	v_addc_co_u32_e32 v13, vcc, -1, v5, vcc
	v_add_co_u32_e32 v18, vcc, 0xffffd000, v4
	s_nop 0
	v_addc_co_u32_e32 v19, vcc, -1, v5, vcc
	v_add_co_u32_e32 v20, vcc, 0xfffde000, v4
	global_load_dwordx2 v[44:45], v[12:13], off
	s_nop 0
	global_load_dwordx2 v[46:47], v[18:19], off
	v_addc_co_u32_e32 v21, vcc, -1, v5, vcc
	v_add_co_u32_e32 v22, vcc, 0xffffe000, v4
	s_nop 0
	v_addc_co_u32_e32 v23, vcc, -1, v5, vcc
	v_add_co_u32_e32 v24, vcc, 0xfffdf000, v4
	global_load_dwordx2 v[48:49], v[20:21], off
	s_nop 0
	global_load_dwordx2 v[50:51], v[22:23], off
	v_addc_co_u32_e32 v25, vcc, -1, v5, vcc
	v_add_co_u32_e32 v26, vcc, s79, v4
	global_load_dwordx2 v[52:53], v[24:25], off
	s_nop 0
	v_addc_co_u32_e32 v27, vcc, -1, v5, vcc
	global_load_dwordx2 v[54:55], v[26:27], off
	v_lshl_add_u64 v[4:5], v[4:5], 0, s[70:71]
	v_add_co_u32_e32 v12, vcc, 0xfffdd000, v4
	global_load_dwordx2 v[56:57], v[4:5], off offset:-4096
	global_load_dwordx2 v[58:59], v[4:5], off
	v_addc_co_u32_e32 v13, vcc, -1, v5, vcc
	v_add_co_u32_e32 v18, vcc, 0xffffd000, v4
	s_nop 0
	v_addc_co_u32_e32 v19, vcc, -1, v5, vcc
	v_add_co_u32_e32 v20, vcc, 0xfffde000, v4
	global_load_dwordx2 v[60:61], v[12:13], off
	s_nop 0
	global_load_dwordx2 v[62:63], v[18:19], off
	v_addc_co_u32_e32 v21, vcc, -1, v5, vcc
	v_add_co_u32_e32 v22, vcc, 0xffffe000, v4
	s_nop 0
	v_addc_co_u32_e32 v23, vcc, -1, v5, vcc
	v_add_co_u32_e32 v24, vcc, 0xfffdf000, v4
	global_load_dwordx2 v[64:65], v[20:21], off
	s_nop 0
	global_load_dwordx2 v[66:67], v[22:23], off
	v_addc_co_u32_e32 v25, vcc, -1, v5, vcc
	v_add_co_u32_e32 v26, vcc, s79, v4
	global_load_dwordx2 v[68:69], v[24:25], off
	s_nop 0
	v_addc_co_u32_e32 v27, vcc, -1, v5, vcc
	global_load_dwordx2 v[70:71], v[26:27], off
	v_lshl_add_u64 v[4:5], v[4:5], 0, s[70:71]
	v_add_co_u32_e32 v12, vcc, 0xfffdd000, v4
	global_load_dwordx2 v[72:73], v[4:5], off offset:-4096
	global_load_dwordx2 v[74:75], v[4:5], off
	v_addc_co_u32_e32 v13, vcc, -1, v5, vcc
	v_add_co_u32_e32 v18, vcc, 0xffffd000, v4
	s_nop 0
	v_addc_co_u32_e32 v19, vcc, -1, v5, vcc
	v_add_co_u32_e32 v20, vcc, 0xfffde000, v4
	global_load_dwordx2 v[76:77], v[12:13], off
	s_nop 0
	global_load_dwordx2 v[78:79], v[18:19], off
	v_addc_co_u32_e32 v21, vcc, -1, v5, vcc
	v_add_co_u32_e32 v22, vcc, 0xffffe000, v4
	s_nop 0
	v_addc_co_u32_e32 v23, vcc, -1, v5, vcc
	v_add_co_u32_e32 v24, vcc, 0xfffdf000, v4
	global_load_dwordx2 v[80:81], v[20:21], off
	s_nop 0
	global_load_dwordx2 v[82:83], v[22:23], off
	v_addc_co_u32_e32 v25, vcc, -1, v5, vcc
	v_add_co_u32_e32 v26, vcc, s79, v4
	global_load_dwordx2 v[84:85], v[24:25], off
	s_nop 0
	v_addc_co_u32_e32 v27, vcc, -1, v5, vcc
	global_load_dwordx2 v[86:87], v[26:27], off
	v_lshl_add_u64 v[4:5], v[4:5], 0, s[70:71]
	v_add_co_u32_e32 v12, vcc, 0xfffdd000, v4
	global_load_dwordx2 v[88:89], v[4:5], off offset:-4096
	global_load_dwordx2 v[90:91], v[4:5], off
	v_addc_co_u32_e32 v13, vcc, -1, v5, vcc
	v_add_co_u32_e32 v18, vcc, 0xffffd000, v4
	s_nop 0
	v_addc_co_u32_e32 v19, vcc, -1, v5, vcc
	v_add_co_u32_e32 v20, vcc, 0xfffde000, v4
	global_load_dwordx2 v[92:93], v[12:13], off
	s_nop 0
	global_load_dwordx2 v[94:95], v[18:19], off
	v_addc_co_u32_e32 v21, vcc, -1, v5, vcc
	v_add_co_u32_e32 v22, vcc, 0xffffe000, v4
	s_nop 0
	v_addc_co_u32_e32 v23, vcc, -1, v5, vcc
	v_add_co_u32_e32 v24, vcc, 0xfffdf000, v4
	global_load_dwordx2 v[96:97], v[20:21], off
	s_nop 0
	global_load_dwordx2 v[98:99], v[22:23], off
	v_addc_co_u32_e32 v25, vcc, -1, v5, vcc
	v_add_co_u32_e32 v26, vcc, s79, v4
	global_load_dwordx2 v[100:101], v[24:25], off
	s_nop 0
	v_addc_co_u32_e32 v27, vcc, -1, v5, vcc
	global_load_dwordx2 v[102:103], v[26:27], off
	v_lshl_add_u64 v[4:5], v[4:5], 0, s[70:71]
	v_add_co_u32_e32 v12, vcc, 0xfffdd000, v4
	global_load_dwordx2 v[104:105], v[4:5], off offset:-4096
	global_load_dwordx2 v[106:107], v[4:5], off
	v_addc_co_u32_e32 v13, vcc, -1, v5, vcc
	v_add_co_u32_e32 v18, vcc, 0xffffd000, v4
	s_nop 0
	v_addc_co_u32_e32 v19, vcc, -1, v5, vcc
	v_add_co_u32_e32 v20, vcc, 0xfffde000, v4
	global_load_dwordx2 v[108:109], v[12:13], off
	s_nop 0
	global_load_dwordx2 v[110:111], v[18:19], off
	v_addc_co_u32_e32 v21, vcc, -1, v5, vcc
	v_add_co_u32_e32 v22, vcc, 0xffffe000, v4
	s_nop 0
	v_addc_co_u32_e32 v23, vcc, -1, v5, vcc
	v_add_co_u32_e32 v24, vcc, 0xfffdf000, v4
	global_load_dwordx2 v[112:113], v[20:21], off
	s_nop 0
	global_load_dwordx2 v[114:115], v[22:23], off
	v_addc_co_u32_e32 v25, vcc, -1, v5, vcc
	v_add_co_u32_e32 v26, vcc, s79, v4
	global_load_dwordx2 v[116:117], v[24:25], off
	s_nop 0
	v_addc_co_u32_e32 v27, vcc, -1, v5, vcc
	global_load_dwordx2 v[118:119], v[26:27], off
	v_lshl_add_u64 v[4:5], v[4:5], 0, s[70:71]
	v_add_co_u32_e32 v12, vcc, 0xfffdd000, v4
	global_load_dwordx2 v[120:121], v[4:5], off offset:-4096
	global_load_dwordx2 v[122:123], v[4:5], off
	v_addc_co_u32_e32 v13, vcc, -1, v5, vcc
	v_add_co_u32_e32 v18, vcc, 0xffffd000, v4
	s_nop 0
	v_addc_co_u32_e32 v19, vcc, -1, v5, vcc
	v_add_co_u32_e32 v20, vcc, 0xfffde000, v4
	global_load_dwordx2 v[124:125], v[12:13], off
	s_nop 0
	global_load_dwordx2 v[126:127], v[18:19], off
	v_addc_co_u32_e32 v21, vcc, -1, v5, vcc
	v_add_co_u32_e32 v22, vcc, 0xffffe000, v4
	s_nop 0
	v_addc_co_u32_e32 v23, vcc, -1, v5, vcc
	v_add_co_u32_e32 v24, vcc, 0xfffdf000, v4
	global_load_dwordx2 v[142:143], v[20:21], off
	s_nop 0
	global_load_dwordx2 v[144:145], v[22:23], off
	v_addc_co_u32_e32 v25, vcc, -1, v5, vcc
	v_add_co_u32_e32 v26, vcc, s79, v4
	global_load_dwordx2 v[146:147], v[24:25], off
	s_nop 0
	v_addc_co_u32_e32 v27, vcc, -1, v5, vcc
	global_load_dwordx2 v[148:149], v[26:27], off
	v_lshl_add_u64 v[4:5], v[4:5], 0, s[70:71]
	v_add_co_u32_e32 v12, vcc, 0xfffdd000, v4
	global_load_dwordx2 v[150:151], v[4:5], off offset:-4096
	global_load_dwordx2 v[152:153], v[4:5], off
	v_addc_co_u32_e32 v13, vcc, -1, v5, vcc
	v_add_co_u32_e32 v18, vcc, 0xffffd000, v4
	s_nop 0
	v_addc_co_u32_e32 v19, vcc, -1, v5, vcc
	v_add_co_u32_e32 v20, vcc, 0xfffde000, v4
	global_load_dwordx2 v[154:155], v[12:13], off
	s_nop 0
	global_load_dwordx2 v[156:157], v[18:19], off
	v_addc_co_u32_e32 v21, vcc, -1, v5, vcc
	v_add_co_u32_e32 v22, vcc, 0xffffe000, v4
	s_nop 0
	v_addc_co_u32_e32 v23, vcc, -1, v5, vcc
	v_add_co_u32_e32 v24, vcc, 0xfffdf000, v4
	global_load_dwordx2 v[158:159], v[20:21], off
	s_nop 0
	global_load_dwordx2 v[160:161], v[22:23], off
	v_addc_co_u32_e32 v25, vcc, -1, v5, vcc
	v_add_co_u32_e32 v26, vcc, s79, v4
	global_load_dwordx2 v[162:163], v[24:25], off
	s_nop 0
	v_addc_co_u32_e32 v27, vcc, -1, v5, vcc
	global_load_dwordx2 v[164:165], v[26:27], off
	v_lshl_add_u64 v[4:5], v[4:5], 0, s[70:71]
	v_add_co_u32_e32 v12, vcc, 0xfffdd000, v4
	global_load_dwordx2 v[166:167], v[4:5], off offset:-4096
	global_load_dwordx2 v[168:169], v[4:5], off
	v_addc_co_u32_e32 v13, vcc, -1, v5, vcc
	v_add_co_u32_e32 v18, vcc, 0xffffd000, v4
	s_nop 0
	v_addc_co_u32_e32 v19, vcc, -1, v5, vcc
	v_add_co_u32_e32 v20, vcc, 0xfffde000, v4
	global_load_dwordx2 v[170:171], v[12:13], off
	s_nop 0
	global_load_dwordx2 v[172:173], v[18:19], off
	v_addc_co_u32_e32 v21, vcc, -1, v5, vcc
	v_add_co_u32_e32 v22, vcc, 0xffffe000, v4
	s_nop 0
	v_addc_co_u32_e32 v23, vcc, -1, v5, vcc
	v_add_co_u32_e32 v24, vcc, 0xfffdf000, v4
	global_load_dwordx2 v[174:175], v[20:21], off
	s_nop 0
	global_load_dwordx2 v[176:177], v[22:23], off
	v_addc_co_u32_e32 v25, vcc, -1, v5, vcc
	v_add_co_u32_e32 v26, vcc, s79, v4
	global_load_dwordx2 v[178:179], v[24:25], off
	s_nop 0
	v_addc_co_u32_e32 v27, vcc, -1, v5, vcc
	global_load_dwordx2 v[180:181], v[26:27], off
	v_lshl_add_u64 v[4:5], v[4:5], 0, s[70:71]
	v_mov_b64_e32 v[4:5], v[140:141]
	s_waitcnt vmcnt(0)
	v_add_co_u32_e32 v12, vcc, 0xfffdd000, v4
	v_mov_b64_e32 v[14:15], v[40:41]
	v_mov_b64_e32 v[16:17], v[42:43]
	v_addc_co_u32_e32 v13, vcc, -1, v5, vcc
	v_add_co_u32_e32 v18, vcc, 0xffffd000, v4
	s_add_i32 s0, s72, s10
	s_nop 0
	v_addc_co_u32_e32 v19, vcc, -1, v5, vcc
	v_add_co_u32_e32 v20, vcc, 0xfffde000, v4
	v_mov_b64_e32 v[12:13], v[44:45]
	s_nop 0
	v_mov_b64_e32 v[18:19], v[46:47]
	v_addc_co_u32_e32 v21, vcc, -1, v5, vcc
	v_add_co_u32_e32 v22, vcc, 0xffffe000, v4
	s_ashr_i32 s1, s0, 31
	s_nop 0
	v_addc_co_u32_e32 v23, vcc, -1, v5, vcc
	v_add_co_u32_e32 v24, vcc, 0xfffdf000, v4
	v_mov_b64_e32 v[20:21], v[48:49]
	s_nop 0
	v_mov_b64_e32 v[22:23], v[50:51]
	v_addc_co_u32_e32 v25, vcc, -1, v5, vcc
	v_add_co_u32_e32 v26, vcc, s79, v4
	v_mov_b64_e32 v[24:25], v[52:53]
	s_nop 0
	v_addc_co_u32_e32 v27, vcc, -1, v5, vcc
	v_mov_b64_e32 v[26:27], v[54:55]
	s_add_i32 s6, s0, 8
	v_mov_b64_e32 v[28:29], s[68:69]
	s_add_i32 s8, s0, 16
	s_add_i32 s12, s0, 24
	s_lshl_b64 s[0:1], s[0:1], 12
	s_ashr_i32 s7, s6, 31
	v_lshl_add_u64 v[30:31], v[2:3], 0, s[0:1]
	s_lshl_b64 s[0:1], s[6:7], 12
	v_lshl_add_u64 v[32:33], v[2:3], 0, s[0:1]
	s_ashr_i32 s9, s8, 31
	s_ashr_i32 s13, s12, 31
	s_lshl_b64 s[6:7], s[8:9], 12
	s_lshl_b64 s[8:9], s[12:13], 12
	v_lshl_add_u64 v[36:37], v[2:3], 0, s[8:9]
	v_lshl_add_u64 v[34:35], v[2:3], 0, s[6:7]
	s_add_i32 s11, s10, 32
	s_cmpk_lt_u32 s10, 0xe0
	s_mov_b32 s10, s11
	v_lshl_add_u64 v[4:5], v[4:5], 0, s[70:71]
	v_pk_fma_f32 v[12:13], v[18:19], s[46:47], v[12:13] neg_lo:[1,0,0] neg_hi:[1,0,0]
	s_nop 0
	v_pk_mul_f32 v[18:19], v[12:13], v[12:13]
	v_pk_fma_f32 v[20:21], v[22:23], s[46:47], v[20:21] neg_lo:[1,0,0] neg_hi:[1,0,0]
	s_nop 0
	v_pk_mul_f32 v[38:39], v[20:21], v[20:21]
	v_mov_b32_e32 v23, v18
	v_mov_b32_e32 v22, v38
	v_mov_b32_e32 v18, v39
	v_pk_fma_f32 v[14:15], v[14:15], s[46:47], v[24:25] neg_lo:[1,0,0] neg_hi:[1,0,0]
	v_pk_add_f32 v[18:19], v[22:23], v[18:19]
	v_pk_mul_f32 v[24:25], v[14:15], v[14:15]
	v_pk_fma_f32 v[16:17], v[16:17], s[46:47], v[26:27] neg_lo:[1,0,0] neg_hi:[1,0,0]
	v_pk_mul_f32 v[26:27], v[16:17], v[16:17]
	v_mov_b32_e32 v23, v24
	v_mov_b32_e32 v22, v26
	v_mov_b32_e32 v24, v27
	v_pk_add_f32 v[22:23], v[22:23], v[24:25]
	s_nop 1
	v_add_f32_dpp v38, v18, v18 quad_perm:[1,0,3,2] row_mask:0xf bank_mask:0xf
	v_add_f32_dpp v39, v19, v19 quad_perm:[1,0,3,2] row_mask:0xf bank_mask:0xf
	v_add_f32_dpp v24, v22, v22 quad_perm:[1,0,3,2] row_mask:0xf bank_mask:0xf
	v_add_f32_dpp v25, v23, v23 quad_perm:[1,0,3,2] row_mask:0xf bank_mask:0xf
	v_add_f32_dpp v18, v38, v38 quad_perm:[2,3,0,1] row_mask:0xf bank_mask:0xf
	v_add_f32_dpp v19, v39, v39 quad_perm:[2,3,0,1] row_mask:0xf bank_mask:0xf
	v_add_f32_dpp v22, v24, v24 quad_perm:[2,3,0,1] row_mask:0xf bank_mask:0xf
	v_add_f32_dpp v23, v25, v25 quad_perm:[2,3,0,1] row_mask:0xf bank_mask:0xf
	v_add_f32_dpp v38, v18, v18 row_ror:4 row_mask:0xf bank_mask:0xf
	v_add_f32_dpp v39, v19, v19 row_ror:4 row_mask:0xf bank_mask:0xf
	v_add_f32_dpp v24, v22, v22 row_ror:4 row_mask:0xf bank_mask:0xf
	v_add_f32_dpp v25, v23, v23 row_ror:4 row_mask:0xf bank_mask:0xf
	v_add_f32_dpp v18, v38, v38 row_ror:8 row_mask:0xf bank_mask:0xf
	v_add_f32_dpp v19, v39, v39 row_ror:8 row_mask:0xf bank_mask:0xf
	v_add_f32_dpp v22, v24, v24 row_ror:8 row_mask:0xf bank_mask:0xf
	v_add_f32_dpp v23, v25, v25 row_ror:8 row_mask:0xf bank_mask:0xf
	s_nop 1
	v_readlane_b32 s100, v18, 0
	v_readlane_b32 s101, v18, 16
	v_readlane_b32 vcc_lo, v18, 32
	v_readlane_b32 vcc_hi, v18, 48
	v_mov_b32_e32 v18, s100
	v_add_f32_e32 v18, s101, v18
	v_add_f32_e32 v18, vcc_lo, v18
	v_add_f32_e32 v18, vcc_hi, v18
	v_readlane_b32 s100, v19, 0
	v_readlane_b32 s101, v19, 16
	v_readlane_b32 vcc_lo, v19, 32
	v_readlane_b32 vcc_hi, v19, 48
	v_mov_b32_e32 v19, s100
	v_add_f32_e32 v19, s101, v19
	v_add_f32_e32 v19, vcc_lo, v19
	v_add_f32_e32 v19, vcc_hi, v19
	v_readlane_b32 s100, v22, 0
	v_readlane_b32 s101, v22, 16
	v_readlane_b32 vcc_lo, v22, 32
	v_readlane_b32 vcc_hi, v22, 48
	v_mov_b32_e32 v22, s100
	v_add_f32_e32 v22, s101, v22
	v_add_f32_e32 v22, vcc_lo, v22
	v_add_f32_e32 v22, vcc_hi, v22
	v_readlane_b32 s100, v23, 0
	v_readlane_b32 s101, v23, 16
	v_readlane_b32 vcc_lo, v23, 32
	v_readlane_b32 vcc_hi, v23, 48
	v_mov_b32_e32 v23, s100
	v_add_f32_e32 v23, s101, v23
	v_add_f32_e32 v23, vcc_lo, v23
	v_add_f32_e32 v23, vcc_hi, v23
	v_pk_fma_f32 v[18:19], v[18:19], s[54:55], v[28:29] op_sel_hi:[1,0,0]
	s_nop 0
	v_mul_f32_e32 v26, 0x4b800000, v19
	v_cmp_gt_f32_e64 s[0:1], s82, v19
	v_mul_f32_e32 v27, 0x4b800000, v18
	v_cmp_gt_f32_e32 vcc, s82, v18
	v_cndmask_b32_e64 v24, v19, v26, s[0:1]
	s_nop 0
	v_cndmask_b32_e32 v25, v18, v27, vcc
	v_pk_fma_f32 v[18:19], v[22:23], s[54:55], v[28:29] op_sel_hi:[1,0,0]
	v_rsq_f32_e32 v22, v24
	v_mul_f32_e32 v24, 0x4b800000, v19
	v_cmp_gt_f32_e64 s[8:9], s82, v19
	v_rsq_f32_e32 v23, v25
	v_mul_f32_e32 v25, 0x4b800000, v18
	v_cmp_gt_f32_e64 s[6:7], s82, v18
	v_cndmask_b32_e64 v19, v19, v24, s[8:9]
	v_rsq_f32_e32 v19, v19
	v_cndmask_b32_e64 v18, v18, v25, s[6:7]
	v_rsq_f32_e32 v18, v18
	v_mul_f32_e32 v24, 0x45800000, v22
	v_cndmask_b32_e64 v22, v22, v24, s[0:1]
	v_mul_f32_e32 v25, 0x45800000, v23
	v_mul_f32_e32 v22, 0x3f4ccccd, v22
	v_cndmask_b32_e32 v23, v23, v25, vcc
	v_mul_f32_e32 v24, 0x45800000, v19
	v_mul_f32_e32 v12, v12, v22
	v_mul_f32_e32 v23, 0x3f4ccccd, v23
	v_mul_f32_e32 v25, 0x45800000, v18
	v_mul_f32_e32 v13, v13, v22
	v_cndmask_b32_e64 v19, v19, v24, s[8:9]
	v_mul_f32_e32 v12, v0, v12
	v_mul_f32_e32 v20, v20, v23
	v_mul_f32_e32 v21, v21, v23
	v_cndmask_b32_e64 v18, v18, v25, s[6:7]
	v_mul_f32_e32 v13, v1, v13
	v_mul_f32_e32 v19, 0x3f4ccccd, v19
	v_cvt_pk_bf16_f32 v12, v12, v13
	v_mul_f32_e32 v20, v0, v20
	v_mul_f32_e32 v21, v1, v21
	v_mul_f32_e32 v18, 0x3f4ccccd, v18
	v_mul_f32_e32 v13, v14, v19
	v_mul_f32_e32 v14, v15, v19
	global_store_dword v[30:31], v12, off
	v_cvt_pk_bf16_f32 v12, v20, v21
	v_mul_f32_e32 v15, v16, v18
	v_mul_f32_e32 v16, v17, v18
	v_mul_f32_e32 v13, v0, v13
	v_mul_f32_e32 v14, v1, v14
	global_store_dword v[32:33], v12, off
	v_cvt_pk_bf16_f32 v12, v13, v14
	v_mul_f32_e32 v15, v0, v15
	v_mul_f32_e32 v16, v1, v16
	global_store_dword v[34:35], v12, off
	v_cvt_pk_bf16_f32 v12, v15, v16
	global_store_dword v[36:37], v12, off
	v_add_co_u32_e32 v12, vcc, 0xfffdd000, v4
	v_mov_b64_e32 v[14:15], v[56:57]
	v_mov_b64_e32 v[16:17], v[58:59]
	v_addc_co_u32_e32 v13, vcc, -1, v5, vcc
	v_add_co_u32_e32 v18, vcc, 0xffffd000, v4
	s_add_i32 s0, s72, s10
	s_nop 0
	v_addc_co_u32_e32 v19, vcc, -1, v5, vcc
	v_add_co_u32_e32 v20, vcc, 0xfffde000, v4
	v_mov_b64_e32 v[12:13], v[60:61]
	s_nop 0
	v_mov_b64_e32 v[18:19], v[62:63]
	v_addc_co_u32_e32 v21, vcc, -1, v5, vcc
	v_add_co_u32_e32 v22, vcc, 0xffffe000, v4
	s_ashr_i32 s1, s0, 31
	s_nop 0
	v_addc_co_u32_e32 v23, vcc, -1, v5, vcc
	v_add_co_u32_e32 v24, vcc, 0xfffdf000, v4
	v_mov_b64_e32 v[20:21], v[64:65]
	s_nop 0
	v_mov_b64_e32 v[22:23], v[66:67]
	v_addc_co_u32_e32 v25, vcc, -1, v5, vcc
	v_add_co_u32_e32 v26, vcc, s79, v4
	v_mov_b64_e32 v[24:25], v[68:69]
	s_nop 0
	v_addc_co_u32_e32 v27, vcc, -1, v5, vcc
	v_mov_b64_e32 v[26:27], v[70:71]
	s_add_i32 s6, s0, 8
	v_mov_b64_e32 v[28:29], s[68:69]
	s_add_i32 s8, s0, 16
	s_add_i32 s12, s0, 24
	s_lshl_b64 s[0:1], s[0:1], 12
	s_ashr_i32 s7, s6, 31
	v_lshl_add_u64 v[30:31], v[2:3], 0, s[0:1]
	s_lshl_b64 s[0:1], s[6:7], 12
	v_lshl_add_u64 v[32:33], v[2:3], 0, s[0:1]
	s_ashr_i32 s9, s8, 31
	s_ashr_i32 s13, s12, 31
	s_lshl_b64 s[6:7], s[8:9], 12
	s_lshl_b64 s[8:9], s[12:13], 12
	v_lshl_add_u64 v[36:37], v[2:3], 0, s[8:9]
	v_lshl_add_u64 v[34:35], v[2:3], 0, s[6:7]
	s_add_i32 s11, s10, 32
	s_cmpk_lt_u32 s10, 0xe0
	s_mov_b32 s10, s11
	v_lshl_add_u64 v[4:5], v[4:5], 0, s[70:71]
	v_pk_fma_f32 v[12:13], v[18:19], s[46:47], v[12:13] neg_lo:[1,0,0] neg_hi:[1,0,0]
	s_nop 0
	v_pk_mul_f32 v[18:19], v[12:13], v[12:13]
	v_pk_fma_f32 v[20:21], v[22:23], s[46:47], v[20:21] neg_lo:[1,0,0] neg_hi:[1,0,0]
	s_nop 0
	v_pk_mul_f32 v[38:39], v[20:21], v[20:21]
	v_mov_b32_e32 v23, v18
	v_mov_b32_e32 v22, v38
	v_mov_b32_e32 v18, v39
	v_pk_fma_f32 v[14:15], v[14:15], s[46:47], v[24:25] neg_lo:[1,0,0] neg_hi:[1,0,0]
	v_pk_add_f32 v[18:19], v[22:23], v[18:19]
	v_pk_mul_f32 v[24:25], v[14:15], v[14:15]
	v_pk_fma_f32 v[16:17], v[16:17], s[46:47], v[26:27] neg_lo:[1,0,0] neg_hi:[1,0,0]
	v_pk_mul_f32 v[26:27], v[16:17], v[16:17]
	v_mov_b32_e32 v23, v24
	v_mov_b32_e32 v22, v26
	v_mov_b32_e32 v24, v27
	v_pk_add_f32 v[22:23], v[22:23], v[24:25]
	s_nop 1
	v_add_f32_dpp v38, v18, v18 quad_perm:[1,0,3,2] row_mask:0xf bank_mask:0xf
	v_add_f32_dpp v39, v19, v19 quad_perm:[1,0,3,2] row_mask:0xf bank_mask:0xf
	v_add_f32_dpp v24, v22, v22 quad_perm:[1,0,3,2] row_mask:0xf bank_mask:0xf
	v_add_f32_dpp v25, v23, v23 quad_perm:[1,0,3,2] row_mask:0xf bank_mask:0xf
	v_add_f32_dpp v18, v38, v38 quad_perm:[2,3,0,1] row_mask:0xf bank_mask:0xf
	v_add_f32_dpp v19, v39, v39 quad_perm:[2,3,0,1] row_mask:0xf bank_mask:0xf
	v_add_f32_dpp v22, v24, v24 quad_perm:[2,3,0,1] row_mask:0xf bank_mask:0xf
	v_add_f32_dpp v23, v25, v25 quad_perm:[2,3,0,1] row_mask:0xf bank_mask:0xf
	v_add_f32_dpp v38, v18, v18 row_ror:4 row_mask:0xf bank_mask:0xf
	v_add_f32_dpp v39, v19, v19 row_ror:4 row_mask:0xf bank_mask:0xf
	v_add_f32_dpp v24, v22, v22 row_ror:4 row_mask:0xf bank_mask:0xf
	v_add_f32_dpp v25, v23, v23 row_ror:4 row_mask:0xf bank_mask:0xf
	v_add_f32_dpp v18, v38, v38 row_ror:8 row_mask:0xf bank_mask:0xf
	v_add_f32_dpp v19, v39, v39 row_ror:8 row_mask:0xf bank_mask:0xf
	v_add_f32_dpp v22, v24, v24 row_ror:8 row_mask:0xf bank_mask:0xf
	v_add_f32_dpp v23, v25, v25 row_ror:8 row_mask:0xf bank_mask:0xf
	s_nop 1
	v_readlane_b32 s100, v18, 0
	v_readlane_b32 s101, v18, 16
	v_readlane_b32 vcc_lo, v18, 32
	v_readlane_b32 vcc_hi, v18, 48
	v_mov_b32_e32 v18, s100
	v_add_f32_e32 v18, s101, v18
	v_add_f32_e32 v18, vcc_lo, v18
	v_add_f32_e32 v18, vcc_hi, v18
	v_readlane_b32 s100, v19, 0
	v_readlane_b32 s101, v19, 16
	v_readlane_b32 vcc_lo, v19, 32
	v_readlane_b32 vcc_hi, v19, 48
	v_mov_b32_e32 v19, s100
	v_add_f32_e32 v19, s101, v19
	v_add_f32_e32 v19, vcc_lo, v19
	v_add_f32_e32 v19, vcc_hi, v19
	v_readlane_b32 s100, v22, 0
	v_readlane_b32 s101, v22, 16
	v_readlane_b32 vcc_lo, v22, 32
	v_readlane_b32 vcc_hi, v22, 48
	v_mov_b32_e32 v22, s100
	v_add_f32_e32 v22, s101, v22
	v_add_f32_e32 v22, vcc_lo, v22
	v_add_f32_e32 v22, vcc_hi, v22
	v_readlane_b32 s100, v23, 0
	v_readlane_b32 s101, v23, 16
	v_readlane_b32 vcc_lo, v23, 32
	v_readlane_b32 vcc_hi, v23, 48
	v_mov_b32_e32 v23, s100
	v_add_f32_e32 v23, s101, v23
	v_add_f32_e32 v23, vcc_lo, v23
	v_add_f32_e32 v23, vcc_hi, v23
	v_pk_fma_f32 v[18:19], v[18:19], s[54:55], v[28:29] op_sel_hi:[1,0,0]
	s_nop 0
	v_mul_f32_e32 v26, 0x4b800000, v19
	v_cmp_gt_f32_e64 s[0:1], s82, v19
	v_mul_f32_e32 v27, 0x4b800000, v18
	v_cmp_gt_f32_e32 vcc, s82, v18
	v_cndmask_b32_e64 v24, v19, v26, s[0:1]
	s_nop 0
	v_cndmask_b32_e32 v25, v18, v27, vcc
	v_pk_fma_f32 v[18:19], v[22:23], s[54:55], v[28:29] op_sel_hi:[1,0,0]
	v_rsq_f32_e32 v22, v24
	v_mul_f32_e32 v24, 0x4b800000, v19
	v_cmp_gt_f32_e64 s[8:9], s82, v19
	v_rsq_f32_e32 v23, v25
	v_mul_f32_e32 v25, 0x4b800000, v18
	v_cmp_gt_f32_e64 s[6:7], s82, v18
	v_cndmask_b32_e64 v19, v19, v24, s[8:9]
	v_rsq_f32_e32 v19, v19
	v_cndmask_b32_e64 v18, v18, v25, s[6:7]
	v_rsq_f32_e32 v18, v18
	v_mul_f32_e32 v24, 0x45800000, v22
	v_cndmask_b32_e64 v22, v22, v24, s[0:1]
	v_mul_f32_e32 v25, 0x45800000, v23
	v_mul_f32_e32 v22, 0x3f4ccccd, v22
	v_cndmask_b32_e32 v23, v23, v25, vcc
	v_mul_f32_e32 v24, 0x45800000, v19
	v_mul_f32_e32 v12, v12, v22
	v_mul_f32_e32 v23, 0x3f4ccccd, v23
	v_mul_f32_e32 v25, 0x45800000, v18
	v_mul_f32_e32 v13, v13, v22
	v_cndmask_b32_e64 v19, v19, v24, s[8:9]
	v_mul_f32_e32 v12, v0, v12
	v_mul_f32_e32 v20, v20, v23
	v_mul_f32_e32 v21, v21, v23
	v_cndmask_b32_e64 v18, v18, v25, s[6:7]
	v_mul_f32_e32 v13, v1, v13
	v_mul_f32_e32 v19, 0x3f4ccccd, v19
	v_cvt_pk_bf16_f32 v12, v12, v13
	v_mul_f32_e32 v20, v0, v20
	v_mul_f32_e32 v21, v1, v21
	v_mul_f32_e32 v18, 0x3f4ccccd, v18
	v_mul_f32_e32 v13, v14, v19
	v_mul_f32_e32 v14, v15, v19
	global_store_dword v[30:31], v12, off
	v_cvt_pk_bf16_f32 v12, v20, v21
	v_mul_f32_e32 v15, v16, v18
	v_mul_f32_e32 v16, v17, v18
	v_mul_f32_e32 v13, v0, v13
	v_mul_f32_e32 v14, v1, v14
	global_store_dword v[32:33], v12, off
	v_cvt_pk_bf16_f32 v12, v13, v14
	v_mul_f32_e32 v15, v0, v15
	v_mul_f32_e32 v16, v1, v16
	global_store_dword v[34:35], v12, off
	v_cvt_pk_bf16_f32 v12, v15, v16
	global_store_dword v[36:37], v12, off
	v_add_co_u32_e32 v12, vcc, 0xfffdd000, v4
	v_mov_b64_e32 v[14:15], v[72:73]
	v_mov_b64_e32 v[16:17], v[74:75]
	v_addc_co_u32_e32 v13, vcc, -1, v5, vcc
	v_add_co_u32_e32 v18, vcc, 0xffffd000, v4
	s_add_i32 s0, s72, s10
	s_nop 0
	v_addc_co_u32_e32 v19, vcc, -1, v5, vcc
	v_add_co_u32_e32 v20, vcc, 0xfffde000, v4
	v_mov_b64_e32 v[12:13], v[76:77]
	s_nop 0
	v_mov_b64_e32 v[18:19], v[78:79]
	v_addc_co_u32_e32 v21, vcc, -1, v5, vcc
	v_add_co_u32_e32 v22, vcc, 0xffffe000, v4
	s_ashr_i32 s1, s0, 31
	s_nop 0
	v_addc_co_u32_e32 v23, vcc, -1, v5, vcc
	v_add_co_u32_e32 v24, vcc, 0xfffdf000, v4
	v_mov_b64_e32 v[20:21], v[80:81]
	s_nop 0
	v_mov_b64_e32 v[22:23], v[82:83]
	v_addc_co_u32_e32 v25, vcc, -1, v5, vcc
	v_add_co_u32_e32 v26, vcc, s79, v4
	v_mov_b64_e32 v[24:25], v[84:85]
	s_nop 0
	v_addc_co_u32_e32 v27, vcc, -1, v5, vcc
	v_mov_b64_e32 v[26:27], v[86:87]
	s_add_i32 s6, s0, 8
	v_mov_b64_e32 v[28:29], s[68:69]
	s_add_i32 s8, s0, 16
	s_add_i32 s12, s0, 24
	s_lshl_b64 s[0:1], s[0:1], 12
	s_ashr_i32 s7, s6, 31
	v_lshl_add_u64 v[30:31], v[2:3], 0, s[0:1]
	s_lshl_b64 s[0:1], s[6:7], 12
	v_lshl_add_u64 v[32:33], v[2:3], 0, s[0:1]
	s_ashr_i32 s9, s8, 31
	s_ashr_i32 s13, s12, 31
	s_lshl_b64 s[6:7], s[8:9], 12
	s_lshl_b64 s[8:9], s[12:13], 12
	v_lshl_add_u64 v[36:37], v[2:3], 0, s[8:9]
	v_lshl_add_u64 v[34:35], v[2:3], 0, s[6:7]
	s_add_i32 s11, s10, 32
	s_cmpk_lt_u32 s10, 0xe0
	s_mov_b32 s10, s11
	v_lshl_add_u64 v[4:5], v[4:5], 0, s[70:71]
	v_pk_fma_f32 v[12:13], v[18:19], s[46:47], v[12:13] neg_lo:[1,0,0] neg_hi:[1,0,0]
	s_nop 0
	v_pk_mul_f32 v[18:19], v[12:13], v[12:13]
	v_pk_fma_f32 v[20:21], v[22:23], s[46:47], v[20:21] neg_lo:[1,0,0] neg_hi:[1,0,0]
	s_nop 0
	v_pk_mul_f32 v[38:39], v[20:21], v[20:21]
	v_mov_b32_e32 v23, v18
	v_mov_b32_e32 v22, v38
	v_mov_b32_e32 v18, v39
	v_pk_fma_f32 v[14:15], v[14:15], s[46:47], v[24:25] neg_lo:[1,0,0] neg_hi:[1,0,0]
	v_pk_add_f32 v[18:19], v[22:23], v[18:19]
	v_pk_mul_f32 v[24:25], v[14:15], v[14:15]
	v_pk_fma_f32 v[16:17], v[16:17], s[46:47], v[26:27] neg_lo:[1,0,0] neg_hi:[1,0,0]
	v_pk_mul_f32 v[26:27], v[16:17], v[16:17]
	v_mov_b32_e32 v23, v24
	v_mov_b32_e32 v22, v26
	v_mov_b32_e32 v24, v27
	v_pk_add_f32 v[22:23], v[22:23], v[24:25]
	s_nop 1
	v_add_f32_dpp v38, v18, v18 quad_perm:[1,0,3,2] row_mask:0xf bank_mask:0xf
	v_add_f32_dpp v39, v19, v19 quad_perm:[1,0,3,2] row_mask:0xf bank_mask:0xf
	v_add_f32_dpp v24, v22, v22 quad_perm:[1,0,3,2] row_mask:0xf bank_mask:0xf
	v_add_f32_dpp v25, v23, v23 quad_perm:[1,0,3,2] row_mask:0xf bank_mask:0xf
	v_add_f32_dpp v18, v38, v38 quad_perm:[2,3,0,1] row_mask:0xf bank_mask:0xf
	v_add_f32_dpp v19, v39, v39 quad_perm:[2,3,0,1] row_mask:0xf bank_mask:0xf
	v_add_f32_dpp v22, v24, v24 quad_perm:[2,3,0,1] row_mask:0xf bank_mask:0xf
	v_add_f32_dpp v23, v25, v25 quad_perm:[2,3,0,1] row_mask:0xf bank_mask:0xf
	v_add_f32_dpp v38, v18, v18 row_ror:4 row_mask:0xf bank_mask:0xf
	v_add_f32_dpp v39, v19, v19 row_ror:4 row_mask:0xf bank_mask:0xf
	v_add_f32_dpp v24, v22, v22 row_ror:4 row_mask:0xf bank_mask:0xf
	v_add_f32_dpp v25, v23, v23 row_ror:4 row_mask:0xf bank_mask:0xf
	v_add_f32_dpp v18, v38, v38 row_ror:8 row_mask:0xf bank_mask:0xf
	v_add_f32_dpp v19, v39, v39 row_ror:8 row_mask:0xf bank_mask:0xf
	v_add_f32_dpp v22, v24, v24 row_ror:8 row_mask:0xf bank_mask:0xf
	v_add_f32_dpp v23, v25, v25 row_ror:8 row_mask:0xf bank_mask:0xf
	s_nop 1
	v_readlane_b32 s100, v18, 0
	v_readlane_b32 s101, v18, 16
	v_readlane_b32 vcc_lo, v18, 32
	v_readlane_b32 vcc_hi, v18, 48
	v_mov_b32_e32 v18, s100
	v_add_f32_e32 v18, s101, v18
	v_add_f32_e32 v18, vcc_lo, v18
	v_add_f32_e32 v18, vcc_hi, v18
	v_readlane_b32 s100, v19, 0
	v_readlane_b32 s101, v19, 16
	v_readlane_b32 vcc_lo, v19, 32
	v_readlane_b32 vcc_hi, v19, 48
	v_mov_b32_e32 v19, s100
	v_add_f32_e32 v19, s101, v19
	v_add_f32_e32 v19, vcc_lo, v19
	v_add_f32_e32 v19, vcc_hi, v19
	v_readlane_b32 s100, v22, 0
	v_readlane_b32 s101, v22, 16
	v_readlane_b32 vcc_lo, v22, 32
	v_readlane_b32 vcc_hi, v22, 48
	v_mov_b32_e32 v22, s100
	v_add_f32_e32 v22, s101, v22
	v_add_f32_e32 v22, vcc_lo, v22
	v_add_f32_e32 v22, vcc_hi, v22
	v_readlane_b32 s100, v23, 0
	v_readlane_b32 s101, v23, 16
	v_readlane_b32 vcc_lo, v23, 32
	v_readlane_b32 vcc_hi, v23, 48
	v_mov_b32_e32 v23, s100
	v_add_f32_e32 v23, s101, v23
	v_add_f32_e32 v23, vcc_lo, v23
	v_add_f32_e32 v23, vcc_hi, v23
	v_pk_fma_f32 v[18:19], v[18:19], s[54:55], v[28:29] op_sel_hi:[1,0,0]
	s_nop 0
	v_mul_f32_e32 v26, 0x4b800000, v19
	v_cmp_gt_f32_e64 s[0:1], s82, v19
	v_mul_f32_e32 v27, 0x4b800000, v18
	v_cmp_gt_f32_e32 vcc, s82, v18
	v_cndmask_b32_e64 v24, v19, v26, s[0:1]
	s_nop 0
	v_cndmask_b32_e32 v25, v18, v27, vcc
	v_pk_fma_f32 v[18:19], v[22:23], s[54:55], v[28:29] op_sel_hi:[1,0,0]
	v_rsq_f32_e32 v22, v24
	v_mul_f32_e32 v24, 0x4b800000, v19
	v_cmp_gt_f32_e64 s[8:9], s82, v19
	v_rsq_f32_e32 v23, v25
	v_mul_f32_e32 v25, 0x4b800000, v18
	v_cmp_gt_f32_e64 s[6:7], s82, v18
	v_cndmask_b32_e64 v19, v19, v24, s[8:9]
	v_rsq_f32_e32 v19, v19
	v_cndmask_b32_e64 v18, v18, v25, s[6:7]
	v_rsq_f32_e32 v18, v18
	v_mul_f32_e32 v24, 0x45800000, v22
	v_cndmask_b32_e64 v22, v22, v24, s[0:1]
	v_mul_f32_e32 v25, 0x45800000, v23
	v_mul_f32_e32 v22, 0x3f4ccccd, v22
	v_cndmask_b32_e32 v23, v23, v25, vcc
	v_mul_f32_e32 v24, 0x45800000, v19
	v_mul_f32_e32 v12, v12, v22
	v_mul_f32_e32 v23, 0x3f4ccccd, v23
	v_mul_f32_e32 v25, 0x45800000, v18
	v_mul_f32_e32 v13, v13, v22
	v_cndmask_b32_e64 v19, v19, v24, s[8:9]
	v_mul_f32_e32 v12, v0, v12
	v_mul_f32_e32 v20, v20, v23
	v_mul_f32_e32 v21, v21, v23
	v_cndmask_b32_e64 v18, v18, v25, s[6:7]
	v_mul_f32_e32 v13, v1, v13
	v_mul_f32_e32 v19, 0x3f4ccccd, v19
	v_cvt_pk_bf16_f32 v12, v12, v13
	v_mul_f32_e32 v20, v0, v20
	v_mul_f32_e32 v21, v1, v21
	v_mul_f32_e32 v18, 0x3f4ccccd, v18
	v_mul_f32_e32 v13, v14, v19
	v_mul_f32_e32 v14, v15, v19
	global_store_dword v[30:31], v12, off
	v_cvt_pk_bf16_f32 v12, v20, v21
	v_mul_f32_e32 v15, v16, v18
	v_mul_f32_e32 v16, v17, v18
	v_mul_f32_e32 v13, v0, v13
	v_mul_f32_e32 v14, v1, v14
	global_store_dword v[32:33], v12, off
	v_cvt_pk_bf16_f32 v12, v13, v14
	v_mul_f32_e32 v15, v0, v15
	v_mul_f32_e32 v16, v1, v16
	global_store_dword v[34:35], v12, off
	v_cvt_pk_bf16_f32 v12, v15, v16
	global_store_dword v[36:37], v12, off
	v_add_co_u32_e32 v12, vcc, 0xfffdd000, v4
	v_mov_b64_e32 v[14:15], v[88:89]
	v_mov_b64_e32 v[16:17], v[90:91]
	v_addc_co_u32_e32 v13, vcc, -1, v5, vcc
	v_add_co_u32_e32 v18, vcc, 0xffffd000, v4
	s_add_i32 s0, s72, s10
	s_nop 0
	v_addc_co_u32_e32 v19, vcc, -1, v5, vcc
	v_add_co_u32_e32 v20, vcc, 0xfffde000, v4
	v_mov_b64_e32 v[12:13], v[92:93]
	s_nop 0
	v_mov_b64_e32 v[18:19], v[94:95]
	v_addc_co_u32_e32 v21, vcc, -1, v5, vcc
	v_add_co_u32_e32 v22, vcc, 0xffffe000, v4
	s_ashr_i32 s1, s0, 31
	s_nop 0
	v_addc_co_u32_e32 v23, vcc, -1, v5, vcc
	v_add_co_u32_e32 v24, vcc, 0xfffdf000, v4
	v_mov_b64_e32 v[20:21], v[96:97]
	s_nop 0
	v_mov_b64_e32 v[22:23], v[98:99]
	v_addc_co_u32_e32 v25, vcc, -1, v5, vcc
	v_add_co_u32_e32 v26, vcc, s79, v4
	v_mov_b64_e32 v[24:25], v[100:101]
	s_nop 0
	v_addc_co_u32_e32 v27, vcc, -1, v5, vcc
	v_mov_b64_e32 v[26:27], v[102:103]
	s_add_i32 s6, s0, 8
	v_mov_b64_e32 v[28:29], s[68:69]
	s_add_i32 s8, s0, 16
	s_add_i32 s12, s0, 24
	s_lshl_b64 s[0:1], s[0:1], 12
	s_ashr_i32 s7, s6, 31
	v_lshl_add_u64 v[30:31], v[2:3], 0, s[0:1]
	s_lshl_b64 s[0:1], s[6:7], 12
	v_lshl_add_u64 v[32:33], v[2:3], 0, s[0:1]
	s_ashr_i32 s9, s8, 31
	s_ashr_i32 s13, s12, 31
	s_lshl_b64 s[6:7], s[8:9], 12
	s_lshl_b64 s[8:9], s[12:13], 12
	v_lshl_add_u64 v[36:37], v[2:3], 0, s[8:9]
	v_lshl_add_u64 v[34:35], v[2:3], 0, s[6:7]
	s_add_i32 s11, s10, 32
	s_cmpk_lt_u32 s10, 0xe0
	s_mov_b32 s10, s11
	v_lshl_add_u64 v[4:5], v[4:5], 0, s[70:71]
	v_pk_fma_f32 v[12:13], v[18:19], s[46:47], v[12:13] neg_lo:[1,0,0] neg_hi:[1,0,0]
	s_nop 0
	v_pk_mul_f32 v[18:19], v[12:13], v[12:13]
	v_pk_fma_f32 v[20:21], v[22:23], s[46:47], v[20:21] neg_lo:[1,0,0] neg_hi:[1,0,0]
	s_nop 0
	v_pk_mul_f32 v[38:39], v[20:21], v[20:21]
	v_mov_b32_e32 v23, v18
	v_mov_b32_e32 v22, v38
	v_mov_b32_e32 v18, v39
	v_pk_fma_f32 v[14:15], v[14:15], s[46:47], v[24:25] neg_lo:[1,0,0] neg_hi:[1,0,0]
	v_pk_add_f32 v[18:19], v[22:23], v[18:19]
	v_pk_mul_f32 v[24:25], v[14:15], v[14:15]
	v_pk_fma_f32 v[16:17], v[16:17], s[46:47], v[26:27] neg_lo:[1,0,0] neg_hi:[1,0,0]
	v_pk_mul_f32 v[26:27], v[16:17], v[16:17]
	v_mov_b32_e32 v23, v24
	v_mov_b32_e32 v22, v26
	v_mov_b32_e32 v24, v27
	v_pk_add_f32 v[22:23], v[22:23], v[24:25]
	s_nop 1
	v_add_f32_dpp v38, v18, v18 quad_perm:[1,0,3,2] row_mask:0xf bank_mask:0xf
	v_add_f32_dpp v39, v19, v19 quad_perm:[1,0,3,2] row_mask:0xf bank_mask:0xf
	v_add_f32_dpp v24, v22, v22 quad_perm:[1,0,3,2] row_mask:0xf bank_mask:0xf
	v_add_f32_dpp v25, v23, v23 quad_perm:[1,0,3,2] row_mask:0xf bank_mask:0xf
	v_add_f32_dpp v18, v38, v38 quad_perm:[2,3,0,1] row_mask:0xf bank_mask:0xf
	v_add_f32_dpp v19, v39, v39 quad_perm:[2,3,0,1] row_mask:0xf bank_mask:0xf
	v_add_f32_dpp v22, v24, v24 quad_perm:[2,3,0,1] row_mask:0xf bank_mask:0xf
	v_add_f32_dpp v23, v25, v25 quad_perm:[2,3,0,1] row_mask:0xf bank_mask:0xf
	v_add_f32_dpp v38, v18, v18 row_ror:4 row_mask:0xf bank_mask:0xf
	v_add_f32_dpp v39, v19, v19 row_ror:4 row_mask:0xf bank_mask:0xf
	v_add_f32_dpp v24, v22, v22 row_ror:4 row_mask:0xf bank_mask:0xf
	v_add_f32_dpp v25, v23, v23 row_ror:4 row_mask:0xf bank_mask:0xf
	v_add_f32_dpp v18, v38, v38 row_ror:8 row_mask:0xf bank_mask:0xf
	v_add_f32_dpp v19, v39, v39 row_ror:8 row_mask:0xf bank_mask:0xf
	v_add_f32_dpp v22, v24, v24 row_ror:8 row_mask:0xf bank_mask:0xf
	v_add_f32_dpp v23, v25, v25 row_ror:8 row_mask:0xf bank_mask:0xf
	s_nop 1
	v_readlane_b32 s100, v18, 0
	v_readlane_b32 s101, v18, 16
	v_readlane_b32 vcc_lo, v18, 32
	v_readlane_b32 vcc_hi, v18, 48
	v_mov_b32_e32 v18, s100
	v_add_f32_e32 v18, s101, v18
	v_add_f32_e32 v18, vcc_lo, v18
	v_add_f32_e32 v18, vcc_hi, v18
	v_readlane_b32 s100, v19, 0
	v_readlane_b32 s101, v19, 16
	v_readlane_b32 vcc_lo, v19, 32
	v_readlane_b32 vcc_hi, v19, 48
	v_mov_b32_e32 v19, s100
	v_add_f32_e32 v19, s101, v19
	v_add_f32_e32 v19, vcc_lo, v19
	v_add_f32_e32 v19, vcc_hi, v19
	v_readlane_b32 s100, v22, 0
	v_readlane_b32 s101, v22, 16
	v_readlane_b32 vcc_lo, v22, 32
	v_readlane_b32 vcc_hi, v22, 48
	v_mov_b32_e32 v22, s100
	v_add_f32_e32 v22, s101, v22
	v_add_f32_e32 v22, vcc_lo, v22
	v_add_f32_e32 v22, vcc_hi, v22
	v_readlane_b32 s100, v23, 0
	v_readlane_b32 s101, v23, 16
	v_readlane_b32 vcc_lo, v23, 32
	v_readlane_b32 vcc_hi, v23, 48
	v_mov_b32_e32 v23, s100
	v_add_f32_e32 v23, s101, v23
	v_add_f32_e32 v23, vcc_lo, v23
	v_add_f32_e32 v23, vcc_hi, v23
	v_pk_fma_f32 v[18:19], v[18:19], s[54:55], v[28:29] op_sel_hi:[1,0,0]
	s_nop 0
	v_mul_f32_e32 v26, 0x4b800000, v19
	v_cmp_gt_f32_e64 s[0:1], s82, v19
	v_mul_f32_e32 v27, 0x4b800000, v18
	v_cmp_gt_f32_e32 vcc, s82, v18
	v_cndmask_b32_e64 v24, v19, v26, s[0:1]
	s_nop 0
	v_cndmask_b32_e32 v25, v18, v27, vcc
	v_pk_fma_f32 v[18:19], v[22:23], s[54:55], v[28:29] op_sel_hi:[1,0,0]
	v_rsq_f32_e32 v22, v24
	v_mul_f32_e32 v24, 0x4b800000, v19
	v_cmp_gt_f32_e64 s[8:9], s82, v19
	v_rsq_f32_e32 v23, v25
	v_mul_f32_e32 v25, 0x4b800000, v18
	v_cmp_gt_f32_e64 s[6:7], s82, v18
	v_cndmask_b32_e64 v19, v19, v24, s[8:9]
	v_rsq_f32_e32 v19, v19
	v_cndmask_b32_e64 v18, v18, v25, s[6:7]
	v_rsq_f32_e32 v18, v18
	v_mul_f32_e32 v24, 0x45800000, v22
	v_cndmask_b32_e64 v22, v22, v24, s[0:1]
	v_mul_f32_e32 v25, 0x45800000, v23
	v_mul_f32_e32 v22, 0x3f4ccccd, v22
	v_cndmask_b32_e32 v23, v23, v25, vcc
	v_mul_f32_e32 v24, 0x45800000, v19
	v_mul_f32_e32 v12, v12, v22
	v_mul_f32_e32 v23, 0x3f4ccccd, v23
	v_mul_f32_e32 v25, 0x45800000, v18
	v_mul_f32_e32 v13, v13, v22
	v_cndmask_b32_e64 v19, v19, v24, s[8:9]
	v_mul_f32_e32 v12, v0, v12
	v_mul_f32_e32 v20, v20, v23
	v_mul_f32_e32 v21, v21, v23
	v_cndmask_b32_e64 v18, v18, v25, s[6:7]
	v_mul_f32_e32 v13, v1, v13
	v_mul_f32_e32 v19, 0x3f4ccccd, v19
	v_cvt_pk_bf16_f32 v12, v12, v13
	v_mul_f32_e32 v20, v0, v20
	v_mul_f32_e32 v21, v1, v21
	v_mul_f32_e32 v18, 0x3f4ccccd, v18
	v_mul_f32_e32 v13, v14, v19
	v_mul_f32_e32 v14, v15, v19
	global_store_dword v[30:31], v12, off
	v_cvt_pk_bf16_f32 v12, v20, v21
	v_mul_f32_e32 v15, v16, v18
	v_mul_f32_e32 v16, v17, v18
	v_mul_f32_e32 v13, v0, v13
	v_mul_f32_e32 v14, v1, v14
	global_store_dword v[32:33], v12, off
	v_cvt_pk_bf16_f32 v12, v13, v14
	v_mul_f32_e32 v15, v0, v15
	v_mul_f32_e32 v16, v1, v16
	global_store_dword v[34:35], v12, off
	v_cvt_pk_bf16_f32 v12, v15, v16
	global_store_dword v[36:37], v12, off
	v_add_co_u32_e32 v12, vcc, 0xfffdd000, v4
	v_mov_b64_e32 v[14:15], v[104:105]
	v_mov_b64_e32 v[16:17], v[106:107]
	v_addc_co_u32_e32 v13, vcc, -1, v5, vcc
	v_add_co_u32_e32 v18, vcc, 0xffffd000, v4
	s_add_i32 s0, s72, s10
	s_nop 0
	v_addc_co_u32_e32 v19, vcc, -1, v5, vcc
	v_add_co_u32_e32 v20, vcc, 0xfffde000, v4
	v_mov_b64_e32 v[12:13], v[108:109]
	s_nop 0
	v_mov_b64_e32 v[18:19], v[110:111]
	v_addc_co_u32_e32 v21, vcc, -1, v5, vcc
	v_add_co_u32_e32 v22, vcc, 0xffffe000, v4
	s_ashr_i32 s1, s0, 31
	s_nop 0
	v_addc_co_u32_e32 v23, vcc, -1, v5, vcc
	v_add_co_u32_e32 v24, vcc, 0xfffdf000, v4
	v_mov_b64_e32 v[20:21], v[112:113]
	s_nop 0
	v_mov_b64_e32 v[22:23], v[114:115]
	v_addc_co_u32_e32 v25, vcc, -1, v5, vcc
	v_add_co_u32_e32 v26, vcc, s79, v4
	v_mov_b64_e32 v[24:25], v[116:117]
	s_nop 0
	v_addc_co_u32_e32 v27, vcc, -1, v5, vcc
	v_mov_b64_e32 v[26:27], v[118:119]
	s_add_i32 s6, s0, 8
	v_mov_b64_e32 v[28:29], s[68:69]
	s_add_i32 s8, s0, 16
	s_add_i32 s12, s0, 24
	s_lshl_b64 s[0:1], s[0:1], 12
	s_ashr_i32 s7, s6, 31
	v_lshl_add_u64 v[30:31], v[2:3], 0, s[0:1]
	s_lshl_b64 s[0:1], s[6:7], 12
	v_lshl_add_u64 v[32:33], v[2:3], 0, s[0:1]
	s_ashr_i32 s9, s8, 31
	s_ashr_i32 s13, s12, 31
	s_lshl_b64 s[6:7], s[8:9], 12
	s_lshl_b64 s[8:9], s[12:13], 12
	v_lshl_add_u64 v[36:37], v[2:3], 0, s[8:9]
	v_lshl_add_u64 v[34:35], v[2:3], 0, s[6:7]
	s_add_i32 s11, s10, 32
	s_cmpk_lt_u32 s10, 0xe0
	s_mov_b32 s10, s11
	v_lshl_add_u64 v[4:5], v[4:5], 0, s[70:71]
	v_pk_fma_f32 v[12:13], v[18:19], s[46:47], v[12:13] neg_lo:[1,0,0] neg_hi:[1,0,0]
	s_nop 0
	v_pk_mul_f32 v[18:19], v[12:13], v[12:13]
	v_pk_fma_f32 v[20:21], v[22:23], s[46:47], v[20:21] neg_lo:[1,0,0] neg_hi:[1,0,0]
	s_nop 0
	v_pk_mul_f32 v[38:39], v[20:21], v[20:21]
	v_mov_b32_e32 v23, v18
	v_mov_b32_e32 v22, v38
	v_mov_b32_e32 v18, v39
	v_pk_fma_f32 v[14:15], v[14:15], s[46:47], v[24:25] neg_lo:[1,0,0] neg_hi:[1,0,0]
	v_pk_add_f32 v[18:19], v[22:23], v[18:19]
	v_pk_mul_f32 v[24:25], v[14:15], v[14:15]
	v_pk_fma_f32 v[16:17], v[16:17], s[46:47], v[26:27] neg_lo:[1,0,0] neg_hi:[1,0,0]
	v_pk_mul_f32 v[26:27], v[16:17], v[16:17]
	v_mov_b32_e32 v23, v24
	v_mov_b32_e32 v22, v26
	v_mov_b32_e32 v24, v27
	v_pk_add_f32 v[22:23], v[22:23], v[24:25]
	s_nop 1
	v_add_f32_dpp v38, v18, v18 quad_perm:[1,0,3,2] row_mask:0xf bank_mask:0xf
	v_add_f32_dpp v39, v19, v19 quad_perm:[1,0,3,2] row_mask:0xf bank_mask:0xf
	v_add_f32_dpp v24, v22, v22 quad_perm:[1,0,3,2] row_mask:0xf bank_mask:0xf
	v_add_f32_dpp v25, v23, v23 quad_perm:[1,0,3,2] row_mask:0xf bank_mask:0xf
	v_add_f32_dpp v18, v38, v38 quad_perm:[2,3,0,1] row_mask:0xf bank_mask:0xf
	v_add_f32_dpp v19, v39, v39 quad_perm:[2,3,0,1] row_mask:0xf bank_mask:0xf
	v_add_f32_dpp v22, v24, v24 quad_perm:[2,3,0,1] row_mask:0xf bank_mask:0xf
	v_add_f32_dpp v23, v25, v25 quad_perm:[2,3,0,1] row_mask:0xf bank_mask:0xf
	v_add_f32_dpp v38, v18, v18 row_ror:4 row_mask:0xf bank_mask:0xf
	v_add_f32_dpp v39, v19, v19 row_ror:4 row_mask:0xf bank_mask:0xf
	v_add_f32_dpp v24, v22, v22 row_ror:4 row_mask:0xf bank_mask:0xf
	v_add_f32_dpp v25, v23, v23 row_ror:4 row_mask:0xf bank_mask:0xf
	v_add_f32_dpp v18, v38, v38 row_ror:8 row_mask:0xf bank_mask:0xf
	v_add_f32_dpp v19, v39, v39 row_ror:8 row_mask:0xf bank_mask:0xf
	v_add_f32_dpp v22, v24, v24 row_ror:8 row_mask:0xf bank_mask:0xf
	v_add_f32_dpp v23, v25, v25 row_ror:8 row_mask:0xf bank_mask:0xf
	s_nop 1
	v_readlane_b32 s100, v18, 0
	v_readlane_b32 s101, v18, 16
	v_readlane_b32 vcc_lo, v18, 32
	v_readlane_b32 vcc_hi, v18, 48
	v_mov_b32_e32 v18, s100
	v_add_f32_e32 v18, s101, v18
	v_add_f32_e32 v18, vcc_lo, v18
	v_add_f32_e32 v18, vcc_hi, v18
	v_readlane_b32 s100, v19, 0
	v_readlane_b32 s101, v19, 16
	v_readlane_b32 vcc_lo, v19, 32
	v_readlane_b32 vcc_hi, v19, 48
	v_mov_b32_e32 v19, s100
	v_add_f32_e32 v19, s101, v19
	v_add_f32_e32 v19, vcc_lo, v19
	v_add_f32_e32 v19, vcc_hi, v19
	v_readlane_b32 s100, v22, 0
	v_readlane_b32 s101, v22, 16
	v_readlane_b32 vcc_lo, v22, 32
	v_readlane_b32 vcc_hi, v22, 48
	v_mov_b32_e32 v22, s100
	v_add_f32_e32 v22, s101, v22
	v_add_f32_e32 v22, vcc_lo, v22
	v_add_f32_e32 v22, vcc_hi, v22
	v_readlane_b32 s100, v23, 0
	v_readlane_b32 s101, v23, 16
	v_readlane_b32 vcc_lo, v23, 32
	v_readlane_b32 vcc_hi, v23, 48
	v_mov_b32_e32 v23, s100
	v_add_f32_e32 v23, s101, v23
	v_add_f32_e32 v23, vcc_lo, v23
	v_add_f32_e32 v23, vcc_hi, v23
	v_pk_fma_f32 v[18:19], v[18:19], s[54:55], v[28:29] op_sel_hi:[1,0,0]
	s_nop 0
	v_mul_f32_e32 v26, 0x4b800000, v19
	v_cmp_gt_f32_e64 s[0:1], s82, v19
	v_mul_f32_e32 v27, 0x4b800000, v18
	v_cmp_gt_f32_e32 vcc, s82, v18
	v_cndmask_b32_e64 v24, v19, v26, s[0:1]
	s_nop 0
	v_cndmask_b32_e32 v25, v18, v27, vcc
	v_pk_fma_f32 v[18:19], v[22:23], s[54:55], v[28:29] op_sel_hi:[1,0,0]
	v_rsq_f32_e32 v22, v24
	v_mul_f32_e32 v24, 0x4b800000, v19
	v_cmp_gt_f32_e64 s[8:9], s82, v19
	v_rsq_f32_e32 v23, v25
	v_mul_f32_e32 v25, 0x4b800000, v18
	v_cmp_gt_f32_e64 s[6:7], s82, v18
	v_cndmask_b32_e64 v19, v19, v24, s[8:9]
	v_rsq_f32_e32 v19, v19
	v_cndmask_b32_e64 v18, v18, v25, s[6:7]
	v_rsq_f32_e32 v18, v18
	v_mul_f32_e32 v24, 0x45800000, v22
	v_cndmask_b32_e64 v22, v22, v24, s[0:1]
	v_mul_f32_e32 v25, 0x45800000, v23
	v_mul_f32_e32 v22, 0x3f4ccccd, v22
	v_cndmask_b32_e32 v23, v23, v25, vcc
	v_mul_f32_e32 v24, 0x45800000, v19
	v_mul_f32_e32 v12, v12, v22
	v_mul_f32_e32 v23, 0x3f4ccccd, v23
	v_mul_f32_e32 v25, 0x45800000, v18
	v_mul_f32_e32 v13, v13, v22
	v_cndmask_b32_e64 v19, v19, v24, s[8:9]
	v_mul_f32_e32 v12, v0, v12
	v_mul_f32_e32 v20, v20, v23
	v_mul_f32_e32 v21, v21, v23
	v_cndmask_b32_e64 v18, v18, v25, s[6:7]
	v_mul_f32_e32 v13, v1, v13
	v_mul_f32_e32 v19, 0x3f4ccccd, v19
	v_cvt_pk_bf16_f32 v12, v12, v13
	v_mul_f32_e32 v20, v0, v20
	v_mul_f32_e32 v21, v1, v21
	v_mul_f32_e32 v18, 0x3f4ccccd, v18
	v_mul_f32_e32 v13, v14, v19
	v_mul_f32_e32 v14, v15, v19
	global_store_dword v[30:31], v12, off
	v_cvt_pk_bf16_f32 v12, v20, v21
	v_mul_f32_e32 v15, v16, v18
	v_mul_f32_e32 v16, v17, v18
	v_mul_f32_e32 v13, v0, v13
	v_mul_f32_e32 v14, v1, v14
	global_store_dword v[32:33], v12, off
	v_cvt_pk_bf16_f32 v12, v13, v14
	v_mul_f32_e32 v15, v0, v15
	v_mul_f32_e32 v16, v1, v16
	global_store_dword v[34:35], v12, off
	v_cvt_pk_bf16_f32 v12, v15, v16
	global_store_dword v[36:37], v12, off
	v_add_co_u32_e32 v12, vcc, 0xfffdd000, v4
	v_mov_b64_e32 v[14:15], v[120:121]
	v_mov_b64_e32 v[16:17], v[122:123]
	v_addc_co_u32_e32 v13, vcc, -1, v5, vcc
	v_add_co_u32_e32 v18, vcc, 0xffffd000, v4
	s_add_i32 s0, s72, s10
	s_nop 0
	v_addc_co_u32_e32 v19, vcc, -1, v5, vcc
	v_add_co_u32_e32 v20, vcc, 0xfffde000, v4
	v_mov_b64_e32 v[12:13], v[124:125]
	s_nop 0
	v_mov_b64_e32 v[18:19], v[126:127]
	v_addc_co_u32_e32 v21, vcc, -1, v5, vcc
	v_add_co_u32_e32 v22, vcc, 0xffffe000, v4
	s_ashr_i32 s1, s0, 31
	s_nop 0
	v_addc_co_u32_e32 v23, vcc, -1, v5, vcc
	v_add_co_u32_e32 v24, vcc, 0xfffdf000, v4
	v_mov_b64_e32 v[20:21], v[142:143]
	s_nop 0
	v_mov_b64_e32 v[22:23], v[144:145]
	v_addc_co_u32_e32 v25, vcc, -1, v5, vcc
	v_add_co_u32_e32 v26, vcc, s79, v4
	v_mov_b64_e32 v[24:25], v[146:147]
	s_nop 0
	v_addc_co_u32_e32 v27, vcc, -1, v5, vcc
	v_mov_b64_e32 v[26:27], v[148:149]
	s_add_i32 s6, s0, 8
	v_mov_b64_e32 v[28:29], s[68:69]
	s_add_i32 s8, s0, 16
	s_add_i32 s12, s0, 24
	s_lshl_b64 s[0:1], s[0:1], 12
	s_ashr_i32 s7, s6, 31
	v_lshl_add_u64 v[30:31], v[2:3], 0, s[0:1]
	s_lshl_b64 s[0:1], s[6:7], 12
	v_lshl_add_u64 v[32:33], v[2:3], 0, s[0:1]
	s_ashr_i32 s9, s8, 31
	s_ashr_i32 s13, s12, 31
	s_lshl_b64 s[6:7], s[8:9], 12
	s_lshl_b64 s[8:9], s[12:13], 12
	v_lshl_add_u64 v[36:37], v[2:3], 0, s[8:9]
	v_lshl_add_u64 v[34:35], v[2:3], 0, s[6:7]
	s_add_i32 s11, s10, 32
	s_cmpk_lt_u32 s10, 0xe0
	s_mov_b32 s10, s11
	v_lshl_add_u64 v[4:5], v[4:5], 0, s[70:71]
	v_pk_fma_f32 v[12:13], v[18:19], s[46:47], v[12:13] neg_lo:[1,0,0] neg_hi:[1,0,0]
	s_nop 0
	v_pk_mul_f32 v[18:19], v[12:13], v[12:13]
	v_pk_fma_f32 v[20:21], v[22:23], s[46:47], v[20:21] neg_lo:[1,0,0] neg_hi:[1,0,0]
	s_nop 0
	v_pk_mul_f32 v[38:39], v[20:21], v[20:21]
	v_mov_b32_e32 v23, v18
	v_mov_b32_e32 v22, v38
	v_mov_b32_e32 v18, v39
	v_pk_fma_f32 v[14:15], v[14:15], s[46:47], v[24:25] neg_lo:[1,0,0] neg_hi:[1,0,0]
	v_pk_add_f32 v[18:19], v[22:23], v[18:19]
	v_pk_mul_f32 v[24:25], v[14:15], v[14:15]
	v_pk_fma_f32 v[16:17], v[16:17], s[46:47], v[26:27] neg_lo:[1,0,0] neg_hi:[1,0,0]
	v_pk_mul_f32 v[26:27], v[16:17], v[16:17]
	v_mov_b32_e32 v23, v24
	v_mov_b32_e32 v22, v26
	v_mov_b32_e32 v24, v27
	v_pk_add_f32 v[22:23], v[22:23], v[24:25]
	s_nop 1
	v_add_f32_dpp v38, v18, v18 quad_perm:[1,0,3,2] row_mask:0xf bank_mask:0xf
	v_add_f32_dpp v39, v19, v19 quad_perm:[1,0,3,2] row_mask:0xf bank_mask:0xf
	v_add_f32_dpp v24, v22, v22 quad_perm:[1,0,3,2] row_mask:0xf bank_mask:0xf
	v_add_f32_dpp v25, v23, v23 quad_perm:[1,0,3,2] row_mask:0xf bank_mask:0xf
	v_add_f32_dpp v18, v38, v38 quad_perm:[2,3,0,1] row_mask:0xf bank_mask:0xf
	v_add_f32_dpp v19, v39, v39 quad_perm:[2,3,0,1] row_mask:0xf bank_mask:0xf
	v_add_f32_dpp v22, v24, v24 quad_perm:[2,3,0,1] row_mask:0xf bank_mask:0xf
	v_add_f32_dpp v23, v25, v25 quad_perm:[2,3,0,1] row_mask:0xf bank_mask:0xf
	v_add_f32_dpp v38, v18, v18 row_ror:4 row_mask:0xf bank_mask:0xf
	v_add_f32_dpp v39, v19, v19 row_ror:4 row_mask:0xf bank_mask:0xf
	v_add_f32_dpp v24, v22, v22 row_ror:4 row_mask:0xf bank_mask:0xf
	v_add_f32_dpp v25, v23, v23 row_ror:4 row_mask:0xf bank_mask:0xf
	v_add_f32_dpp v18, v38, v38 row_ror:8 row_mask:0xf bank_mask:0xf
	v_add_f32_dpp v19, v39, v39 row_ror:8 row_mask:0xf bank_mask:0xf
	v_add_f32_dpp v22, v24, v24 row_ror:8 row_mask:0xf bank_mask:0xf
	v_add_f32_dpp v23, v25, v25 row_ror:8 row_mask:0xf bank_mask:0xf
	s_nop 1
	v_readlane_b32 s100, v18, 0
	v_readlane_b32 s101, v18, 16
	v_readlane_b32 vcc_lo, v18, 32
	v_readlane_b32 vcc_hi, v18, 48
	v_mov_b32_e32 v18, s100
	v_add_f32_e32 v18, s101, v18
	v_add_f32_e32 v18, vcc_lo, v18
	v_add_f32_e32 v18, vcc_hi, v18
	v_readlane_b32 s100, v19, 0
	v_readlane_b32 s101, v19, 16
	v_readlane_b32 vcc_lo, v19, 32
	v_readlane_b32 vcc_hi, v19, 48
	v_mov_b32_e32 v19, s100
	v_add_f32_e32 v19, s101, v19
	v_add_f32_e32 v19, vcc_lo, v19
	v_add_f32_e32 v19, vcc_hi, v19
	v_readlane_b32 s100, v22, 0
	v_readlane_b32 s101, v22, 16
	v_readlane_b32 vcc_lo, v22, 32
	v_readlane_b32 vcc_hi, v22, 48
	v_mov_b32_e32 v22, s100
	v_add_f32_e32 v22, s101, v22
	v_add_f32_e32 v22, vcc_lo, v22
	v_add_f32_e32 v22, vcc_hi, v22
	v_readlane_b32 s100, v23, 0
	v_readlane_b32 s101, v23, 16
	v_readlane_b32 vcc_lo, v23, 32
	v_readlane_b32 vcc_hi, v23, 48
	v_mov_b32_e32 v23, s100
	v_add_f32_e32 v23, s101, v23
	v_add_f32_e32 v23, vcc_lo, v23
	v_add_f32_e32 v23, vcc_hi, v23
	v_pk_fma_f32 v[18:19], v[18:19], s[54:55], v[28:29] op_sel_hi:[1,0,0]
	s_nop 0
	v_mul_f32_e32 v26, 0x4b800000, v19
	v_cmp_gt_f32_e64 s[0:1], s82, v19
	v_mul_f32_e32 v27, 0x4b800000, v18
	v_cmp_gt_f32_e32 vcc, s82, v18
	v_cndmask_b32_e64 v24, v19, v26, s[0:1]
	s_nop 0
	v_cndmask_b32_e32 v25, v18, v27, vcc
	v_pk_fma_f32 v[18:19], v[22:23], s[54:55], v[28:29] op_sel_hi:[1,0,0]
	v_rsq_f32_e32 v22, v24
	v_mul_f32_e32 v24, 0x4b800000, v19
	v_cmp_gt_f32_e64 s[8:9], s82, v19
	v_rsq_f32_e32 v23, v25
	v_mul_f32_e32 v25, 0x4b800000, v18
	v_cmp_gt_f32_e64 s[6:7], s82, v18
	v_cndmask_b32_e64 v19, v19, v24, s[8:9]
	v_rsq_f32_e32 v19, v19
	v_cndmask_b32_e64 v18, v18, v25, s[6:7]
	v_rsq_f32_e32 v18, v18
	v_mul_f32_e32 v24, 0x45800000, v22
	v_cndmask_b32_e64 v22, v22, v24, s[0:1]
	v_mul_f32_e32 v25, 0x45800000, v23
	v_mul_f32_e32 v22, 0x3f4ccccd, v22
	v_cndmask_b32_e32 v23, v23, v25, vcc
	v_mul_f32_e32 v24, 0x45800000, v19
	v_mul_f32_e32 v12, v12, v22
	v_mul_f32_e32 v23, 0x3f4ccccd, v23
	v_mul_f32_e32 v25, 0x45800000, v18
	v_mul_f32_e32 v13, v13, v22
	v_cndmask_b32_e64 v19, v19, v24, s[8:9]
	v_mul_f32_e32 v12, v0, v12
	v_mul_f32_e32 v20, v20, v23
	v_mul_f32_e32 v21, v21, v23
	v_cndmask_b32_e64 v18, v18, v25, s[6:7]
	v_mul_f32_e32 v13, v1, v13
	v_mul_f32_e32 v19, 0x3f4ccccd, v19
	v_cvt_pk_bf16_f32 v12, v12, v13
	v_mul_f32_e32 v20, v0, v20
	v_mul_f32_e32 v21, v1, v21
	v_mul_f32_e32 v18, 0x3f4ccccd, v18
	v_mul_f32_e32 v13, v14, v19
	v_mul_f32_e32 v14, v15, v19
	global_store_dword v[30:31], v12, off
	v_cvt_pk_bf16_f32 v12, v20, v21
	v_mul_f32_e32 v15, v16, v18
	v_mul_f32_e32 v16, v17, v18
	v_mul_f32_e32 v13, v0, v13
	v_mul_f32_e32 v14, v1, v14
	global_store_dword v[32:33], v12, off
	v_cvt_pk_bf16_f32 v12, v13, v14
	v_mul_f32_e32 v15, v0, v15
	v_mul_f32_e32 v16, v1, v16
	global_store_dword v[34:35], v12, off
	v_cvt_pk_bf16_f32 v12, v15, v16
	global_store_dword v[36:37], v12, off
	v_add_co_u32_e32 v12, vcc, 0xfffdd000, v4
	v_mov_b64_e32 v[14:15], v[150:151]
	v_mov_b64_e32 v[16:17], v[152:153]
	v_addc_co_u32_e32 v13, vcc, -1, v5, vcc
	v_add_co_u32_e32 v18, vcc, 0xffffd000, v4
	s_add_i32 s0, s72, s10
	s_nop 0
	v_addc_co_u32_e32 v19, vcc, -1, v5, vcc
	v_add_co_u32_e32 v20, vcc, 0xfffde000, v4
	v_mov_b64_e32 v[12:13], v[154:155]
	s_nop 0
	v_mov_b64_e32 v[18:19], v[156:157]
	v_addc_co_u32_e32 v21, vcc, -1, v5, vcc
	v_add_co_u32_e32 v22, vcc, 0xffffe000, v4
	s_ashr_i32 s1, s0, 31
	s_nop 0
	v_addc_co_u32_e32 v23, vcc, -1, v5, vcc
	v_add_co_u32_e32 v24, vcc, 0xfffdf000, v4
	v_mov_b64_e32 v[20:21], v[158:159]
	s_nop 0
	v_mov_b64_e32 v[22:23], v[160:161]
	v_addc_co_u32_e32 v25, vcc, -1, v5, vcc
	v_add_co_u32_e32 v26, vcc, s79, v4
	v_mov_b64_e32 v[24:25], v[162:163]
	s_nop 0
	v_addc_co_u32_e32 v27, vcc, -1, v5, vcc
	v_mov_b64_e32 v[26:27], v[164:165]
	s_add_i32 s6, s0, 8
	v_mov_b64_e32 v[28:29], s[68:69]
	s_add_i32 s8, s0, 16
	s_add_i32 s12, s0, 24
	s_lshl_b64 s[0:1], s[0:1], 12
	s_ashr_i32 s7, s6, 31
	v_lshl_add_u64 v[30:31], v[2:3], 0, s[0:1]
	s_lshl_b64 s[0:1], s[6:7], 12
	v_lshl_add_u64 v[32:33], v[2:3], 0, s[0:1]
	s_ashr_i32 s9, s8, 31
	s_ashr_i32 s13, s12, 31
	s_lshl_b64 s[6:7], s[8:9], 12
	s_lshl_b64 s[8:9], s[12:13], 12
	v_lshl_add_u64 v[36:37], v[2:3], 0, s[8:9]
	v_lshl_add_u64 v[34:35], v[2:3], 0, s[6:7]
	s_add_i32 s11, s10, 32
	s_cmpk_lt_u32 s10, 0xe0
	s_mov_b32 s10, s11
	v_lshl_add_u64 v[4:5], v[4:5], 0, s[70:71]
	v_pk_fma_f32 v[12:13], v[18:19], s[46:47], v[12:13] neg_lo:[1,0,0] neg_hi:[1,0,0]
	s_nop 0
	v_pk_mul_f32 v[18:19], v[12:13], v[12:13]
	v_pk_fma_f32 v[20:21], v[22:23], s[46:47], v[20:21] neg_lo:[1,0,0] neg_hi:[1,0,0]
	s_nop 0
	v_pk_mul_f32 v[38:39], v[20:21], v[20:21]
	v_mov_b32_e32 v23, v18
	v_mov_b32_e32 v22, v38
	v_mov_b32_e32 v18, v39
	v_pk_fma_f32 v[14:15], v[14:15], s[46:47], v[24:25] neg_lo:[1,0,0] neg_hi:[1,0,0]
	v_pk_add_f32 v[18:19], v[22:23], v[18:19]
	v_pk_mul_f32 v[24:25], v[14:15], v[14:15]
	v_pk_fma_f32 v[16:17], v[16:17], s[46:47], v[26:27] neg_lo:[1,0,0] neg_hi:[1,0,0]
	v_pk_mul_f32 v[26:27], v[16:17], v[16:17]
	v_mov_b32_e32 v23, v24
	v_mov_b32_e32 v22, v26
	v_mov_b32_e32 v24, v27
	v_pk_add_f32 v[22:23], v[22:23], v[24:25]
	s_nop 1
	v_add_f32_dpp v38, v18, v18 quad_perm:[1,0,3,2] row_mask:0xf bank_mask:0xf
	v_add_f32_dpp v39, v19, v19 quad_perm:[1,0,3,2] row_mask:0xf bank_mask:0xf
	v_add_f32_dpp v24, v22, v22 quad_perm:[1,0,3,2] row_mask:0xf bank_mask:0xf
	v_add_f32_dpp v25, v23, v23 quad_perm:[1,0,3,2] row_mask:0xf bank_mask:0xf
	v_add_f32_dpp v18, v38, v38 quad_perm:[2,3,0,1] row_mask:0xf bank_mask:0xf
	v_add_f32_dpp v19, v39, v39 quad_perm:[2,3,0,1] row_mask:0xf bank_mask:0xf
	v_add_f32_dpp v22, v24, v24 quad_perm:[2,3,0,1] row_mask:0xf bank_mask:0xf
	v_add_f32_dpp v23, v25, v25 quad_perm:[2,3,0,1] row_mask:0xf bank_mask:0xf
	v_add_f32_dpp v38, v18, v18 row_ror:4 row_mask:0xf bank_mask:0xf
	v_add_f32_dpp v39, v19, v19 row_ror:4 row_mask:0xf bank_mask:0xf
	v_add_f32_dpp v24, v22, v22 row_ror:4 row_mask:0xf bank_mask:0xf
	v_add_f32_dpp v25, v23, v23 row_ror:4 row_mask:0xf bank_mask:0xf
	v_add_f32_dpp v18, v38, v38 row_ror:8 row_mask:0xf bank_mask:0xf
	v_add_f32_dpp v19, v39, v39 row_ror:8 row_mask:0xf bank_mask:0xf
	v_add_f32_dpp v22, v24, v24 row_ror:8 row_mask:0xf bank_mask:0xf
	v_add_f32_dpp v23, v25, v25 row_ror:8 row_mask:0xf bank_mask:0xf
	s_nop 1
	v_readlane_b32 s100, v18, 0
	v_readlane_b32 s101, v18, 16
	v_readlane_b32 vcc_lo, v18, 32
	v_readlane_b32 vcc_hi, v18, 48
	v_mov_b32_e32 v18, s100
	v_add_f32_e32 v18, s101, v18
	v_add_f32_e32 v18, vcc_lo, v18
	v_add_f32_e32 v18, vcc_hi, v18
	v_readlane_b32 s100, v19, 0
	v_readlane_b32 s101, v19, 16
	v_readlane_b32 vcc_lo, v19, 32
	v_readlane_b32 vcc_hi, v19, 48
	v_mov_b32_e32 v19, s100
	v_add_f32_e32 v19, s101, v19
	v_add_f32_e32 v19, vcc_lo, v19
	v_add_f32_e32 v19, vcc_hi, v19
	v_readlane_b32 s100, v22, 0
	v_readlane_b32 s101, v22, 16
	v_readlane_b32 vcc_lo, v22, 32
	v_readlane_b32 vcc_hi, v22, 48
	v_mov_b32_e32 v22, s100
	v_add_f32_e32 v22, s101, v22
	v_add_f32_e32 v22, vcc_lo, v22
	v_add_f32_e32 v22, vcc_hi, v22
	v_readlane_b32 s100, v23, 0
	v_readlane_b32 s101, v23, 16
	v_readlane_b32 vcc_lo, v23, 32
	v_readlane_b32 vcc_hi, v23, 48
	v_mov_b32_e32 v23, s100
	v_add_f32_e32 v23, s101, v23
	v_add_f32_e32 v23, vcc_lo, v23
	v_add_f32_e32 v23, vcc_hi, v23
	v_pk_fma_f32 v[18:19], v[18:19], s[54:55], v[28:29] op_sel_hi:[1,0,0]
	s_nop 0
	v_mul_f32_e32 v26, 0x4b800000, v19
	v_cmp_gt_f32_e64 s[0:1], s82, v19
	v_mul_f32_e32 v27, 0x4b800000, v18
	v_cmp_gt_f32_e32 vcc, s82, v18
	v_cndmask_b32_e64 v24, v19, v26, s[0:1]
	s_nop 0
	v_cndmask_b32_e32 v25, v18, v27, vcc
	v_pk_fma_f32 v[18:19], v[22:23], s[54:55], v[28:29] op_sel_hi:[1,0,0]
	v_rsq_f32_e32 v22, v24
	v_mul_f32_e32 v24, 0x4b800000, v19
	v_cmp_gt_f32_e64 s[8:9], s82, v19
	v_rsq_f32_e32 v23, v25
	v_mul_f32_e32 v25, 0x4b800000, v18
	v_cmp_gt_f32_e64 s[6:7], s82, v18
	v_cndmask_b32_e64 v19, v19, v24, s[8:9]
	v_rsq_f32_e32 v19, v19
	v_cndmask_b32_e64 v18, v18, v25, s[6:7]
	v_rsq_f32_e32 v18, v18
	v_mul_f32_e32 v24, 0x45800000, v22
	v_cndmask_b32_e64 v22, v22, v24, s[0:1]
	v_mul_f32_e32 v25, 0x45800000, v23
	v_mul_f32_e32 v22, 0x3f4ccccd, v22
	v_cndmask_b32_e32 v23, v23, v25, vcc
	v_mul_f32_e32 v24, 0x45800000, v19
	v_mul_f32_e32 v12, v12, v22
	v_mul_f32_e32 v23, 0x3f4ccccd, v23
	v_mul_f32_e32 v25, 0x45800000, v18
	v_mul_f32_e32 v13, v13, v22
	v_cndmask_b32_e64 v19, v19, v24, s[8:9]
	v_mul_f32_e32 v12, v0, v12
	v_mul_f32_e32 v20, v20, v23
	v_mul_f32_e32 v21, v21, v23
	v_cndmask_b32_e64 v18, v18, v25, s[6:7]
	v_mul_f32_e32 v13, v1, v13
	v_mul_f32_e32 v19, 0x3f4ccccd, v19
	v_cvt_pk_bf16_f32 v12, v12, v13
	v_mul_f32_e32 v20, v0, v20
	v_mul_f32_e32 v21, v1, v21
	v_mul_f32_e32 v18, 0x3f4ccccd, v18
	v_mul_f32_e32 v13, v14, v19
	v_mul_f32_e32 v14, v15, v19
	global_store_dword v[30:31], v12, off
	v_cvt_pk_bf16_f32 v12, v20, v21
	v_mul_f32_e32 v15, v16, v18
	v_mul_f32_e32 v16, v17, v18
	v_mul_f32_e32 v13, v0, v13
	v_mul_f32_e32 v14, v1, v14
	global_store_dword v[32:33], v12, off
	v_cvt_pk_bf16_f32 v12, v13, v14
	v_mul_f32_e32 v15, v0, v15
	v_mul_f32_e32 v16, v1, v16
	global_store_dword v[34:35], v12, off
	v_cvt_pk_bf16_f32 v12, v15, v16
	global_store_dword v[36:37], v12, off
	v_add_co_u32_e32 v12, vcc, 0xfffdd000, v4
	v_mov_b64_e32 v[14:15], v[166:167]
	v_mov_b64_e32 v[16:17], v[168:169]
	v_addc_co_u32_e32 v13, vcc, -1, v5, vcc
	v_add_co_u32_e32 v18, vcc, 0xffffd000, v4
	s_add_i32 s0, s72, s10
	s_nop 0
	v_addc_co_u32_e32 v19, vcc, -1, v5, vcc
	v_add_co_u32_e32 v20, vcc, 0xfffde000, v4
	v_mov_b64_e32 v[12:13], v[170:171]
	s_nop 0
	v_mov_b64_e32 v[18:19], v[172:173]
	v_addc_co_u32_e32 v21, vcc, -1, v5, vcc
	v_add_co_u32_e32 v22, vcc, 0xffffe000, v4
	s_ashr_i32 s1, s0, 31
	s_nop 0
	v_addc_co_u32_e32 v23, vcc, -1, v5, vcc
	v_add_co_u32_e32 v24, vcc, 0xfffdf000, v4
	v_mov_b64_e32 v[20:21], v[174:175]
	s_nop 0
	v_mov_b64_e32 v[22:23], v[176:177]
	v_addc_co_u32_e32 v25, vcc, -1, v5, vcc
	v_add_co_u32_e32 v26, vcc, s79, v4
	v_mov_b64_e32 v[24:25], v[178:179]
	s_nop 0
	v_addc_co_u32_e32 v27, vcc, -1, v5, vcc
	v_mov_b64_e32 v[26:27], v[180:181]
	s_add_i32 s6, s0, 8
	v_mov_b64_e32 v[28:29], s[68:69]
	s_add_i32 s8, s0, 16
	s_add_i32 s12, s0, 24
	s_lshl_b64 s[0:1], s[0:1], 12
	s_ashr_i32 s7, s6, 31
	v_lshl_add_u64 v[30:31], v[2:3], 0, s[0:1]
	s_lshl_b64 s[0:1], s[6:7], 12
	v_lshl_add_u64 v[32:33], v[2:3], 0, s[0:1]
	s_ashr_i32 s9, s8, 31
	s_ashr_i32 s13, s12, 31
	s_lshl_b64 s[6:7], s[8:9], 12
	s_lshl_b64 s[8:9], s[12:13], 12
	v_lshl_add_u64 v[36:37], v[2:3], 0, s[8:9]
	v_lshl_add_u64 v[34:35], v[2:3], 0, s[6:7]
	s_add_i32 s11, s10, 32
	s_cmpk_lt_u32 s10, 0xe0
	s_mov_b32 s10, s11
	v_lshl_add_u64 v[4:5], v[4:5], 0, s[70:71]
	v_pk_fma_f32 v[12:13], v[18:19], s[46:47], v[12:13] neg_lo:[1,0,0] neg_hi:[1,0,0]
	s_nop 0
	v_pk_mul_f32 v[18:19], v[12:13], v[12:13]
	v_pk_fma_f32 v[20:21], v[22:23], s[46:47], v[20:21] neg_lo:[1,0,0] neg_hi:[1,0,0]
	s_nop 0
	v_pk_mul_f32 v[38:39], v[20:21], v[20:21]
	v_mov_b32_e32 v23, v18
	v_mov_b32_e32 v22, v38
	v_mov_b32_e32 v18, v39
	v_pk_fma_f32 v[14:15], v[14:15], s[46:47], v[24:25] neg_lo:[1,0,0] neg_hi:[1,0,0]
	v_pk_add_f32 v[18:19], v[22:23], v[18:19]
	v_pk_mul_f32 v[24:25], v[14:15], v[14:15]
	v_pk_fma_f32 v[16:17], v[16:17], s[46:47], v[26:27] neg_lo:[1,0,0] neg_hi:[1,0,0]
	v_pk_mul_f32 v[26:27], v[16:17], v[16:17]
	v_mov_b32_e32 v23, v24
	v_mov_b32_e32 v22, v26
	v_mov_b32_e32 v24, v27
	v_pk_add_f32 v[22:23], v[22:23], v[24:25]
	s_nop 1
	v_add_f32_dpp v38, v18, v18 quad_perm:[1,0,3,2] row_mask:0xf bank_mask:0xf
	v_add_f32_dpp v39, v19, v19 quad_perm:[1,0,3,2] row_mask:0xf bank_mask:0xf
	v_add_f32_dpp v24, v22, v22 quad_perm:[1,0,3,2] row_mask:0xf bank_mask:0xf
	v_add_f32_dpp v25, v23, v23 quad_perm:[1,0,3,2] row_mask:0xf bank_mask:0xf
	v_add_f32_dpp v18, v38, v38 quad_perm:[2,3,0,1] row_mask:0xf bank_mask:0xf
	v_add_f32_dpp v19, v39, v39 quad_perm:[2,3,0,1] row_mask:0xf bank_mask:0xf
	v_add_f32_dpp v22, v24, v24 quad_perm:[2,3,0,1] row_mask:0xf bank_mask:0xf
	v_add_f32_dpp v23, v25, v25 quad_perm:[2,3,0,1] row_mask:0xf bank_mask:0xf
	v_add_f32_dpp v38, v18, v18 row_ror:4 row_mask:0xf bank_mask:0xf
	v_add_f32_dpp v39, v19, v19 row_ror:4 row_mask:0xf bank_mask:0xf
	v_add_f32_dpp v24, v22, v22 row_ror:4 row_mask:0xf bank_mask:0xf
	v_add_f32_dpp v25, v23, v23 row_ror:4 row_mask:0xf bank_mask:0xf
	v_add_f32_dpp v18, v38, v38 row_ror:8 row_mask:0xf bank_mask:0xf
	v_add_f32_dpp v19, v39, v39 row_ror:8 row_mask:0xf bank_mask:0xf
	v_add_f32_dpp v22, v24, v24 row_ror:8 row_mask:0xf bank_mask:0xf
	v_add_f32_dpp v23, v25, v25 row_ror:8 row_mask:0xf bank_mask:0xf
	s_nop 1
	v_readlane_b32 s100, v18, 0
	v_readlane_b32 s101, v18, 16
	v_readlane_b32 vcc_lo, v18, 32
	v_readlane_b32 vcc_hi, v18, 48
	v_mov_b32_e32 v18, s100
	v_add_f32_e32 v18, s101, v18
	v_add_f32_e32 v18, vcc_lo, v18
	v_add_f32_e32 v18, vcc_hi, v18
	v_readlane_b32 s100, v19, 0
	v_readlane_b32 s101, v19, 16
	v_readlane_b32 vcc_lo, v19, 32
	v_readlane_b32 vcc_hi, v19, 48
	v_mov_b32_e32 v19, s100
	v_add_f32_e32 v19, s101, v19
	v_add_f32_e32 v19, vcc_lo, v19
	v_add_f32_e32 v19, vcc_hi, v19
	v_readlane_b32 s100, v22, 0
	v_readlane_b32 s101, v22, 16
	v_readlane_b32 vcc_lo, v22, 32
	v_readlane_b32 vcc_hi, v22, 48
	v_mov_b32_e32 v22, s100
	v_add_f32_e32 v22, s101, v22
	v_add_f32_e32 v22, vcc_lo, v22
	v_add_f32_e32 v22, vcc_hi, v22
	v_readlane_b32 s100, v23, 0
	v_readlane_b32 s101, v23, 16
	v_readlane_b32 vcc_lo, v23, 32
	v_readlane_b32 vcc_hi, v23, 48
	v_mov_b32_e32 v23, s100
	v_add_f32_e32 v23, s101, v23
	v_add_f32_e32 v23, vcc_lo, v23
	v_add_f32_e32 v23, vcc_hi, v23
	v_pk_fma_f32 v[18:19], v[18:19], s[54:55], v[28:29] op_sel_hi:[1,0,0]
	s_nop 0
	v_mul_f32_e32 v26, 0x4b800000, v19
	v_cmp_gt_f32_e64 s[0:1], s82, v19
	v_mul_f32_e32 v27, 0x4b800000, v18
	v_cmp_gt_f32_e32 vcc, s82, v18
	v_cndmask_b32_e64 v24, v19, v26, s[0:1]
	s_nop 0
	v_cndmask_b32_e32 v25, v18, v27, vcc
	v_pk_fma_f32 v[18:19], v[22:23], s[54:55], v[28:29] op_sel_hi:[1,0,0]
	v_rsq_f32_e32 v22, v24
	v_mul_f32_e32 v24, 0x4b800000, v19
	v_cmp_gt_f32_e64 s[8:9], s82, v19
	v_rsq_f32_e32 v23, v25
	v_mul_f32_e32 v25, 0x4b800000, v18
	v_cmp_gt_f32_e64 s[6:7], s82, v18
	v_cndmask_b32_e64 v19, v19, v24, s[8:9]
	v_rsq_f32_e32 v19, v19
	v_cndmask_b32_e64 v18, v18, v25, s[6:7]
	v_rsq_f32_e32 v18, v18
	v_mul_f32_e32 v24, 0x45800000, v22
	v_cndmask_b32_e64 v22, v22, v24, s[0:1]
	v_mul_f32_e32 v25, 0x45800000, v23
	v_mul_f32_e32 v22, 0x3f4ccccd, v22
	v_cndmask_b32_e32 v23, v23, v25, vcc
	v_mul_f32_e32 v24, 0x45800000, v19
	v_mul_f32_e32 v12, v12, v22
	v_mul_f32_e32 v23, 0x3f4ccccd, v23
	v_mul_f32_e32 v25, 0x45800000, v18
	v_mul_f32_e32 v13, v13, v22
	v_cndmask_b32_e64 v19, v19, v24, s[8:9]
	v_mul_f32_e32 v12, v0, v12
	v_mul_f32_e32 v20, v20, v23
	v_mul_f32_e32 v21, v21, v23
	v_cndmask_b32_e64 v18, v18, v25, s[6:7]
	v_mul_f32_e32 v13, v1, v13
	v_mul_f32_e32 v19, 0x3f4ccccd, v19
	v_cvt_pk_bf16_f32 v12, v12, v13
	v_mul_f32_e32 v20, v0, v20
	v_mul_f32_e32 v21, v1, v21
	v_mul_f32_e32 v18, 0x3f4ccccd, v18
	v_mul_f32_e32 v13, v14, v19
	v_mul_f32_e32 v14, v15, v19
	global_store_dword v[30:31], v12, off
	v_cvt_pk_bf16_f32 v12, v20, v21
	v_mul_f32_e32 v15, v16, v18
	v_mul_f32_e32 v16, v17, v18
	v_mul_f32_e32 v13, v0, v13
	v_mul_f32_e32 v14, v1, v14
	global_store_dword v[32:33], v12, off
	v_cvt_pk_bf16_f32 v12, v13, v14
	v_mul_f32_e32 v15, v0, v15
	v_mul_f32_e32 v16, v1, v16
	global_store_dword v[34:35], v12, off
	v_cvt_pk_bf16_f32 v12, v15, v16
	global_store_dword v[36:37], v12, off
	s_branch .LBB0_455
